# vAA + the four GEMM K-loop heads aligned to 64-byte instruction-cache lines (.p2align 6)
# baseline (speedup 1.0000x reference)
.Lpeel_108:
	s_add_u32 s0, s40, 0xfffc0080
	s_addc_u32 s1, s41, -1
	s_add_i32 s68, 0, 0x10000
	s_cmp_eq_u32 s47, 12
	s_cselect_b32 s5, s6, s1
	s_cselect_b32 s4, s7, s0
	s_cselect_b32 s1, s37, s46
	s_cselect_b32 s0, s42, s43
	s_add_i32 s70, 0, 0x14000
	v_add_u32_e32 v60, s68, v250
	v_add_u32_e32 v124, s70, v250
	ds_read_b128 v[40:43], v60
	ds_read_b128 v[44:47], v60 offset:1024
	ds_read_b128 v[56:59], v60 offset:2048
	ds_read_b128 v[60:63], v60 offset:3072
	ds_read_b128 v[104:107], v124
	ds_read_b128 v[112:115], v124 offset:1024
	ds_read_b128 v[120:123], v124 offset:2048
	ds_read_b128 v[124:127], v124 offset:3072
	s_add_i32 m0, s20, 0xc000
	ds_read_b128 v[152:155], v251
	ds_read_b128 v[156:159], v251 offset:1024
	ds_read_b128 v[168:171], v251 offset:2048
	ds_read_b128 v[172:175], v251 offset:3072
	ds_read_b128 v[200:203], v251 offset:4096
	ds_read_b128 v[204:207], v251 offset:5120
	ds_read_b128 v[208:211], v251 offset:6144
	ds_read_b128 v[212:215], v251 offset:7168
	global_load_lds_dwordx4 v196, s[40:41]
	s_add_i32 m0, s20, 0xe000
	s_nop 0
	global_load_lds_dwordx4 v198, s[40:41]
	s_waitcnt vmcnt(8)
	s_waitcnt lgkmcnt(0)
	s_barrier
	s_waitcnt lgkmcnt(0)
	v_mfma_f32_16x16x32_bf16 v[164:167], v[40:43], v[152:155], 0
	v_mfma_f32_16x16x32_bf16 v[160:163], v[56:59], v[152:155], 0
	v_mfma_f32_16x16x32_bf16 v[116:119], v[40:43], v[168:171], 0
	v_mfma_f32_16x16x32_bf16 v[108:111], v[56:59], v[168:171], 0
	v_mfma_f32_16x16x32_bf16 v[140:143], v[40:43], v[200:203], 0
	v_mfma_f32_16x16x32_bf16 v[136:139], v[56:59], v[200:203], 0
	v_mfma_f32_16x16x32_bf16 v[92:95], v[40:43], v[208:211], 0
	v_mfma_f32_16x16x32_bf16 v[88:91], v[56:59], v[208:211], 0
	v_mfma_f32_16x16x32_bf16 v[164:167], v[44:47], v[156:159], v[164:167]
	v_mfma_f32_16x16x32_bf16 v[160:163], v[60:63], v[156:159], v[160:163]
	v_mfma_f32_16x16x32_bf16 v[116:119], v[44:47], v[172:175], v[116:119]
	v_mfma_f32_16x16x32_bf16 v[108:111], v[60:63], v[172:175], v[108:111]
	v_mfma_f32_16x16x32_bf16 v[140:143], v[44:47], v[204:207], v[140:143]
	v_mfma_f32_16x16x32_bf16 v[136:139], v[60:63], v[204:207], v[136:139]
	v_mfma_f32_16x16x32_bf16 v[92:95], v[44:47], v[212:215], v[92:95]
	v_mfma_f32_16x16x32_bf16 v[88:91], v[60:63], v[212:215], v[88:91]
	v_mfma_f32_16x16x32_bf16 v[148:151], v[104:107], v[152:155], 0
	v_mfma_f32_16x16x32_bf16 v[144:147], v[120:123], v[152:155], 0
	v_mfma_f32_16x16x32_bf16 v[100:103], v[104:107], v[168:171], 0
	v_mfma_f32_16x16x32_bf16 v[96:99], v[120:123], v[168:171], 0
	v_mfma_f32_16x16x32_bf16 v[132:135], v[104:107], v[200:203], 0
	v_mfma_f32_16x16x32_bf16 v[128:131], v[120:123], v[200:203], 0
	v_mfma_f32_16x16x32_bf16 v[84:87], v[104:107], v[208:211], 0
	v_mfma_f32_16x16x32_bf16 v[80:83], v[120:123], v[208:211], 0
	v_mfma_f32_16x16x32_bf16 v[148:151], v[112:115], v[156:159], v[148:151]
	v_mfma_f32_16x16x32_bf16 v[144:147], v[124:127], v[156:159], v[144:147]
	v_mfma_f32_16x16x32_bf16 v[100:103], v[112:115], v[172:175], v[100:103]
	v_mfma_f32_16x16x32_bf16 v[96:99], v[124:127], v[172:175], v[96:99]
	v_mfma_f32_16x16x32_bf16 v[132:135], v[112:115], v[204:207], v[132:135]
	v_mfma_f32_16x16x32_bf16 v[128:131], v[124:127], v[204:207], v[128:131]
	v_mfma_f32_16x16x32_bf16 v[84:87], v[112:115], v[212:215], v[84:87]
	v_mfma_f32_16x16x32_bf16 v[80:83], v[124:127], v[212:215], v[80:83]
	s_barrier
	s_add_i32 s68, s68, s27
	v_lshl_add_u64 v[178:179], s[0:1], 0, v[176:177]
	s_mov_b32 m0, s68
	ds_read_b128 v[152:155], v251 offset:16384
	ds_read_b128 v[156:159], v251 offset:17408
	ds_read_b128 v[168:171], v251 offset:18432
	ds_read_b128 v[172:175], v251 offset:19456
	ds_read_b128 v[200:203], v251 offset:20480
	ds_read_b128 v[204:207], v251 offset:21504
	ds_read_b128 v[208:211], v251 offset:22528
	ds_read_b128 v[212:215], v251 offset:23552
	global_load_lds_dwordx4 v176, s[0:1]
	s_add_i32 m0, s68, 0x2000
	s_add_u32 s68, s0, 0x40000
	v_lshl_add_u64 v[180:181], s[0:1], 0, v[190:191]
	s_addc_u32 s69, s1, 0
	s_add_i32 s70, s70, s27
	global_load_lds_dwordx4 v190, s[0:1]
	s_mov_b32 m0, s70
	v_lshl_add_u64 v[188:189], s[4:5], 0, v[192:193]
	global_load_lds_dwordx4 v176, s[68:69]
	s_add_i32 m0, s70, 0x2000
	s_nop 0
	global_load_lds_dwordx4 v190, s[68:69]
	v_lshl_add_u64 v[186:187], s[4:5], 0, v[194:195]
	s_mov_b32 m0, s20
	s_nop 0
	global_load_lds_dwordx4 v194, s[4:5]
	s_mov_b32 m0, s12
	s_nop 0
	global_load_lds_dwordx4 v192, s[4:5]
	s_waitcnt vmcnt(8)
	s_waitcnt lgkmcnt(0)
	s_barrier
	s_waitcnt lgkmcnt(0)
	v_mfma_f32_16x16x32_bf16 v[76:79], v[40:43], v[152:155], 0
	v_mfma_f32_16x16x32_bf16 v[72:75], v[56:59], v[152:155], 0
	v_mfma_f32_16x16x32_bf16 v[52:55], v[40:43], v[168:171], 0
	v_mfma_f32_16x16x32_bf16 v[48:51], v[56:59], v[168:171], 0
	v_mfma_f32_16x16x32_bf16 v[28:31], v[40:43], v[200:203], 0
	v_mfma_f32_16x16x32_bf16 v[24:27], v[56:59], v[200:203], 0
	v_mfma_f32_16x16x32_bf16 v[12:15], v[40:43], v[208:211], 0
	v_mfma_f32_16x16x32_bf16 v[8:11], v[56:59], v[208:211], 0
	v_mfma_f32_16x16x32_bf16 v[76:79], v[44:47], v[156:159], v[76:79]
	v_mfma_f32_16x16x32_bf16 v[72:75], v[60:63], v[156:159], v[72:75]
	v_mfma_f32_16x16x32_bf16 v[52:55], v[44:47], v[172:175], v[52:55]
	v_mfma_f32_16x16x32_bf16 v[48:51], v[60:63], v[172:175], v[48:51]
	v_mfma_f32_16x16x32_bf16 v[28:31], v[44:47], v[204:207], v[28:31]
	v_mfma_f32_16x16x32_bf16 v[24:27], v[60:63], v[204:207], v[24:27]
	v_mfma_f32_16x16x32_bf16 v[12:15], v[44:47], v[212:215], v[12:15]
	v_mfma_f32_16x16x32_bf16 v[8:11], v[60:63], v[212:215], v[8:11]
	v_mfma_f32_16x16x32_bf16 v[36:39], v[104:107], v[168:171], 0
	v_mfma_f32_16x16x32_bf16 v[32:35], v[120:123], v[168:171], 0
	v_mfma_f32_16x16x32_bf16 v[20:23], v[104:107], v[200:203], 0
	v_mfma_f32_16x16x32_bf16 v[16:19], v[120:123], v[200:203], 0
	v_mfma_f32_16x16x32_bf16 v[4:7], v[104:107], v[208:211], 0
	v_mfma_f32_16x16x32_bf16 v[0:3], v[120:123], v[208:211], 0
	v_mfma_f32_16x16x32_bf16 v[40:43], v[104:107], v[152:155], 0
	v_mfma_f32_16x16x32_bf16 v[44:47], v[120:123], v[152:155], 0
	v_mfma_f32_16x16x32_bf16 v[36:39], v[112:115], v[172:175], v[36:39]
	v_mfma_f32_16x16x32_bf16 v[32:35], v[124:127], v[172:175], v[32:35]
	v_mfma_f32_16x16x32_bf16 v[20:23], v[112:115], v[204:207], v[20:23]
	v_mfma_f32_16x16x32_bf16 v[16:19], v[124:127], v[204:207], v[16:19]
	v_mfma_f32_16x16x32_bf16 v[4:7], v[112:115], v[212:215], v[4:7]
	v_mfma_f32_16x16x32_bf16 v[0:3], v[124:127], v[212:215], v[0:3]
	v_mfma_f32_16x16x32_bf16 v[40:43], v[112:115], v[156:159], v[40:43]
	v_mfma_f32_16x16x32_bf16 v[44:47], v[124:127], v[156:159], v[44:47]
	s_barrier
	s_add_i32 s68, 0, 0x18000
	s_add_i32 s69, 0, 0x1c000
	v_add_u32_e32 v68, s68, v250
	v_add_u32_e32 v124, s69, v250
	ds_read_b128 v[56:59], v68
	ds_read_b128 v[60:63], v68 offset:1024
	ds_read_b128 v[64:67], v68 offset:2048
	ds_read_b128 v[68:71], v68 offset:3072
	ds_read_b128 v[104:107], v124
	ds_read_b128 v[112:115], v124 offset:1024
	ds_read_b128 v[120:123], v124 offset:2048
	ds_read_b128 v[124:127], v124 offset:3072
	s_add_u32 s4, s4, 0x40000
	s_addc_u32 s5, s5, 0
	s_mov_b32 m0, s60
	ds_read_b128 v[152:155], v251 offset:32768
	ds_read_b128 v[156:159], v251 offset:33792
	ds_read_b128 v[168:171], v251 offset:34816
	ds_read_b128 v[172:175], v251 offset:35840
	ds_read_b128 v[200:203], v251 offset:36864
	ds_read_b128 v[204:207], v251 offset:37888
	ds_read_b128 v[208:211], v251 offset:38912
	ds_read_b128 v[212:215], v251 offset:39936
	global_load_lds_dwordx4 v194, s[4:5]
	s_mov_b32 m0, s61
	s_nop 0
	global_load_lds_dwordx4 v192, s[4:5]
	s_waitcnt vmcnt(8)
	s_waitcnt lgkmcnt(0)
	s_barrier
	s_waitcnt lgkmcnt(0)
	v_mfma_f32_16x16x32_bf16 v[164:167], v[56:59], v[152:155], v[164:167]
	v_mfma_f32_16x16x32_bf16 v[160:163], v[64:67], v[152:155], v[160:163]
	v_mfma_f32_16x16x32_bf16 v[116:119], v[56:59], v[168:171], v[116:119]
	v_mfma_f32_16x16x32_bf16 v[108:111], v[64:67], v[168:171], v[108:111]
	v_mfma_f32_16x16x32_bf16 v[140:143], v[56:59], v[200:203], v[140:143]
	v_mfma_f32_16x16x32_bf16 v[136:139], v[64:67], v[200:203], v[136:139]
	v_mfma_f32_16x16x32_bf16 v[92:95], v[56:59], v[208:211], v[92:95]
	v_mfma_f32_16x16x32_bf16 v[88:91], v[64:67], v[208:211], v[88:91]
	v_mfma_f32_16x16x32_bf16 v[164:167], v[60:63], v[156:159], v[164:167]
	v_mfma_f32_16x16x32_bf16 v[160:163], v[68:71], v[156:159], v[160:163]
	v_mfma_f32_16x16x32_bf16 v[116:119], v[60:63], v[172:175], v[116:119]
	v_mfma_f32_16x16x32_bf16 v[108:111], v[68:71], v[172:175], v[108:111]
	v_mfma_f32_16x16x32_bf16 v[140:143], v[60:63], v[204:207], v[140:143]
	v_mfma_f32_16x16x32_bf16 v[136:139], v[68:71], v[204:207], v[136:139]
	v_mfma_f32_16x16x32_bf16 v[92:95], v[60:63], v[212:215], v[92:95]
	v_mfma_f32_16x16x32_bf16 v[88:91], v[68:71], v[212:215], v[88:91]
	v_mfma_f32_16x16x32_bf16 v[148:151], v[104:107], v[152:155], v[148:151]
	v_mfma_f32_16x16x32_bf16 v[144:147], v[120:123], v[152:155], v[144:147]
	v_mfma_f32_16x16x32_bf16 v[100:103], v[104:107], v[168:171], v[100:103]
	v_mfma_f32_16x16x32_bf16 v[96:99], v[120:123], v[168:171], v[96:99]
	v_mfma_f32_16x16x32_bf16 v[132:135], v[104:107], v[200:203], v[132:135]
	v_mfma_f32_16x16x32_bf16 v[128:131], v[120:123], v[200:203], v[128:131]
	v_mfma_f32_16x16x32_bf16 v[84:87], v[104:107], v[208:211], v[84:87]
	v_mfma_f32_16x16x32_bf16 v[80:83], v[120:123], v[208:211], v[80:83]
	v_mfma_f32_16x16x32_bf16 v[148:151], v[112:115], v[156:159], v[148:151]
	v_mfma_f32_16x16x32_bf16 v[144:147], v[124:127], v[156:159], v[144:147]
	v_mfma_f32_16x16x32_bf16 v[100:103], v[112:115], v[172:175], v[100:103]
	v_mfma_f32_16x16x32_bf16 v[96:99], v[124:127], v[172:175], v[96:99]
	v_mfma_f32_16x16x32_bf16 v[132:135], v[112:115], v[204:207], v[132:135]
	v_mfma_f32_16x16x32_bf16 v[128:131], v[124:127], v[204:207], v[128:131]
	v_mfma_f32_16x16x32_bf16 v[84:87], v[112:115], v[212:215], v[84:87]
	v_mfma_f32_16x16x32_bf16 v[80:83], v[124:127], v[212:215], v[80:83]
	s_barrier
	s_add_i32 s4, s68, s27
	v_lshl_add_u64 v[178:179], v[178:179], 0, s[82:83]
	s_mov_b32 m0, s4
	ds_read_b128 v[152:155], v251 offset:49152
	ds_read_b128 v[156:159], v251 offset:50176
	ds_read_b128 v[168:171], v251 offset:51200
	ds_read_b128 v[172:175], v251 offset:52224
	ds_read_b128 v[200:203], v251 offset:53248
	ds_read_b128 v[204:207], v251 offset:54272
	ds_read_b128 v[208:211], v251 offset:55296
	ds_read_b128 v[212:215], v251 offset:56320
	global_load_lds_dwordx4 v[178:179], off
	s_add_i32 m0, s4, 0x2000
	s_add_u32 s0, s0, 0x40080
	v_lshl_add_u64 v[178:179], v[180:181], 0, s[82:83]
	s_addc_u32 s1, s1, 0
	s_add_i32 s4, s69, s27
	global_load_lds_dwordx4 v[178:179], off
	s_mov_b32 m0, s4
	s_nop 0
	global_load_lds_dwordx4 v176, s[0:1]
	s_add_i32 m0, s4, 0x2000
	s_nop 0
	global_load_lds_dwordx4 v190, s[0:1]
	v_lshl_add_u64 v[178:179], v[186:187], 0, s[82:83]
	s_mov_b32 m0, s64
	s_nop 0
	global_load_lds_dwordx4 v[178:179], off
	v_lshl_add_u64 v[178:179], v[188:189], 0, s[82:83]
	s_mov_b32 m0, s65
	s_nop 0
	global_load_lds_dwordx4 v[178:179], off
	s_waitcnt vmcnt(8)
	s_waitcnt lgkmcnt(0)
	s_barrier
	s_waitcnt lgkmcnt(0)
	v_mfma_f32_16x16x32_bf16 v[76:79], v[56:59], v[152:155], v[76:79]
	v_mfma_f32_16x16x32_bf16 v[72:75], v[64:67], v[152:155], v[72:75]
	v_mfma_f32_16x16x32_bf16 v[52:55], v[56:59], v[168:171], v[52:55]
	v_mfma_f32_16x16x32_bf16 v[48:51], v[64:67], v[168:171], v[48:51]
	v_mfma_f32_16x16x32_bf16 v[28:31], v[56:59], v[200:203], v[28:31]
	v_mfma_f32_16x16x32_bf16 v[24:27], v[64:67], v[200:203], v[24:27]
	v_mfma_f32_16x16x32_bf16 v[12:15], v[56:59], v[208:211], v[12:15]
	v_mfma_f32_16x16x32_bf16 v[8:11], v[64:67], v[208:211], v[8:11]
	v_mfma_f32_16x16x32_bf16 v[76:79], v[60:63], v[156:159], v[76:79]
	v_mfma_f32_16x16x32_bf16 v[72:75], v[68:71], v[156:159], v[72:75]
	v_mfma_f32_16x16x32_bf16 v[52:55], v[60:63], v[172:175], v[52:55]
	v_mfma_f32_16x16x32_bf16 v[48:51], v[68:71], v[172:175], v[48:51]
	v_mfma_f32_16x16x32_bf16 v[28:31], v[60:63], v[204:207], v[28:31]
	v_mfma_f32_16x16x32_bf16 v[24:27], v[68:71], v[204:207], v[24:27]
	v_mfma_f32_16x16x32_bf16 v[12:15], v[60:63], v[212:215], v[12:15]
	v_mfma_f32_16x16x32_bf16 v[8:11], v[68:71], v[212:215], v[8:11]
	v_mfma_f32_16x16x32_bf16 v[40:43], v[104:107], v[152:155], v[40:43]
	v_mfma_f32_16x16x32_bf16 v[68:71], v[112:115], v[156:159], v[40:43]
	v_mfma_f32_16x16x32_bf16 v[40:43], v[120:123], v[152:155], v[44:47]
	v_mfma_f32_16x16x32_bf16 v[36:39], v[104:107], v[168:171], v[36:39]
	v_mfma_f32_16x16x32_bf16 v[32:35], v[120:123], v[168:171], v[32:35]
	v_mfma_f32_16x16x32_bf16 v[20:23], v[104:107], v[200:203], v[20:23]
	v_mfma_f32_16x16x32_bf16 v[16:19], v[120:123], v[200:203], v[16:19]
	v_mfma_f32_16x16x32_bf16 v[4:7], v[104:107], v[208:211], v[4:7]
	v_mfma_f32_16x16x32_bf16 v[0:3], v[120:123], v[208:211], v[0:3]
	v_mfma_f32_16x16x32_bf16 v[64:67], v[124:127], v[156:159], v[40:43]
	v_mfma_f32_16x16x32_bf16 v[36:39], v[112:115], v[172:175], v[36:39]
	v_mfma_f32_16x16x32_bf16 v[32:35], v[124:127], v[172:175], v[32:35]
	v_mfma_f32_16x16x32_bf16 v[20:23], v[112:115], v[204:207], v[20:23]
	v_mfma_f32_16x16x32_bf16 v[16:19], v[124:127], v[204:207], v[16:19]
	v_mfma_f32_16x16x32_bf16 v[4:7], v[112:115], v[212:215], v[4:7]
	v_mfma_f32_16x16x32_bf16 v[0:3], v[124:127], v[212:215], v[0:3]
	s_barrier
	s_add_i32 s47, s47, 2
	s_add_u32 s40, s40, 0x100
	s_addc_u32 s41, s41, 0
	s_add_u32 s43, s43, 0x100
	s_addc_u32 s46, s46, 0
	s_cmp_gt_u32 s47, 13
	.p2align	6

.LBB0_661:
	s_ashr_i32 s53, s52, 31
	s_lshl_b64 s[6:7], s[52:53], 19
	s_add_u32 s54, s12, s6
	s_addc_u32 s55, s20, s7
	s_and_b64 s[6:7], s[42:43], exec
	s_cselect_b32 s6, s55, s5
	s_cselect_b32 s7, s54, s4
	s_ashr_i32 s41, s40, 31
	s_lshl_b64 s[44:45], s[40:41], 19
	s_add_u32 s56, s27, s44
	s_addc_u32 s57, s60, s45
	s_and_b64 s[44:45], s[42:43], exec
	s_cselect_b32 s41, s57, s1
	s_cselect_b32 s53, s56, s0
	s_add_u32 s44, s4, 0x40080
	s_addc_u32 s45, s5, 0
	s_add_u32 s74, s0, 0x100
	v_mov_b32_e32 v0, 0
	s_addc_u32 s75, s1, 0
	s_mov_b32 s86, -2
	v_mov_b32_e32 v1, v0
	v_mov_b32_e32 v2, v0
	v_mov_b32_e32 v3, v0
	v_mov_b32_e32 v4, v0
	v_mov_b32_e32 v5, v0
	v_mov_b32_e32 v6, v0
	v_mov_b32_e32 v7, v0
	v_mov_b32_e32 v16, v0
	v_mov_b32_e32 v17, v0
	v_mov_b32_e32 v18, v0
	v_mov_b32_e32 v19, v0
	v_mov_b32_e32 v20, v0
	v_mov_b32_e32 v21, v0
	v_mov_b32_e32 v22, v0
	v_mov_b32_e32 v23, v0
	v_mov_b32_e32 v32, v0
	v_mov_b32_e32 v33, v0
	v_mov_b32_e32 v34, v0
	v_mov_b32_e32 v35, v0
	v_mov_b32_e32 v36, v0
	v_mov_b32_e32 v37, v0
	v_mov_b32_e32 v38, v0
	v_mov_b32_e32 v39, v0
	v_mov_b32_e32 v48, v0
	v_mov_b32_e32 v49, v0
	v_mov_b32_e32 v50, v0
	v_mov_b32_e32 v51, v0
	v_mov_b32_e32 v52, v0
	v_mov_b32_e32 v53, v0
	v_mov_b32_e32 v54, v0
	v_mov_b32_e32 v55, v0
	v_mov_b32_e32 v8, v0
	v_mov_b32_e32 v9, v0
	v_mov_b32_e32 v10, v0
	v_mov_b32_e32 v11, v0
	v_mov_b32_e32 v12, v0
	v_mov_b32_e32 v13, v0
	v_mov_b32_e32 v14, v0
	v_mov_b32_e32 v15, v0
	v_mov_b32_e32 v24, v0
	v_mov_b32_e32 v25, v0
	v_mov_b32_e32 v26, v0
	v_mov_b32_e32 v27, v0
	v_mov_b32_e32 v28, v0
	v_mov_b32_e32 v29, v0
	v_mov_b32_e32 v30, v0
	v_mov_b32_e32 v31, v0
	v_mov_b32_e32 v40, v0
	v_mov_b32_e32 v41, v0
	v_mov_b32_e32 v42, v0
	v_mov_b32_e32 v43, v0
	v_mov_b32_e32 v44, v0
	v_mov_b32_e32 v45, v0
	v_mov_b32_e32 v46, v0
	v_mov_b32_e32 v47, v0
	v_mov_b32_e32 v56, v0
	v_mov_b32_e32 v57, v0
	v_mov_b32_e32 v58, v0
	v_mov_b32_e32 v59, v0
	v_mov_b32_e32 v60, v0
	v_mov_b32_e32 v61, v0
	v_mov_b32_e32 v62, v0
	v_mov_b32_e32 v63, v0
	v_mov_b32_e32 v64, v0
	v_mov_b32_e32 v65, v0
	v_mov_b32_e32 v66, v0
	v_mov_b32_e32 v67, v0
	v_mov_b32_e32 v68, v0
	v_mov_b32_e32 v69, v0
	v_mov_b32_e32 v70, v0
	v_mov_b32_e32 v71, v0
	v_mov_b32_e32 v80, v0
	v_mov_b32_e32 v81, v0
	v_mov_b32_e32 v82, v0
	v_mov_b32_e32 v83, v0
	v_mov_b32_e32 v84, v0
	v_mov_b32_e32 v85, v0
	v_mov_b32_e32 v86, v0
	v_mov_b32_e32 v87, v0
	v_mov_b32_e32 v96, v0
	v_mov_b32_e32 v97, v0
	v_mov_b32_e32 v98, v0
	v_mov_b32_e32 v99, v0
	v_mov_b32_e32 v100, v0
	v_mov_b32_e32 v101, v0
	v_mov_b32_e32 v102, v0
	v_mov_b32_e32 v103, v0
	v_mov_b32_e32 v112, v0
	v_mov_b32_e32 v113, v0
	v_mov_b32_e32 v114, v0
	v_mov_b32_e32 v115, v0
	v_mov_b32_e32 v116, v0
	v_mov_b32_e32 v117, v0
	v_mov_b32_e32 v118, v0
	v_mov_b32_e32 v119, v0
	v_mov_b32_e32 v72, v0
	v_mov_b32_e32 v73, v0
	v_mov_b32_e32 v74, v0
	v_mov_b32_e32 v75, v0
	v_mov_b32_e32 v76, v0
	v_mov_b32_e32 v77, v0
	v_mov_b32_e32 v78, v0
	v_mov_b32_e32 v79, v0
	v_mov_b32_e32 v88, v0
	v_mov_b32_e32 v89, v0
	v_mov_b32_e32 v90, v0
	v_mov_b32_e32 v91, v0
	v_mov_b32_e32 v92, v0
	v_mov_b32_e32 v93, v0
	v_mov_b32_e32 v94, v0
	v_mov_b32_e32 v95, v0
	v_mov_b32_e32 v104, v0
	v_mov_b32_e32 v105, v0
	v_mov_b32_e32 v106, v0
	v_mov_b32_e32 v107, v0
	v_mov_b32_e32 v108, v0
	v_mov_b32_e32 v109, v0
	v_mov_b32_e32 v110, v0
	v_mov_b32_e32 v111, v0
	v_mov_b32_e32 v120, v0
	v_mov_b32_e32 v121, v0
	v_mov_b32_e32 v122, v0
	v_mov_b32_e32 v123, v0
	v_mov_b32_e32 v124, v0
	v_mov_b32_e32 v125, v0
	v_mov_b32_e32 v126, v0
	v_mov_b32_e32 v127, v0
	.p2align	6

.Lpeel_748:
	s_add_u32 s0, s44, 0xfffc0080
	s_addc_u32 s1, s45, -1
	s_add_i32 s74, 0, 0x10000
	s_cmp_eq_u32 s73, 12
	s_cselect_b32 s5, s6, s1
	s_cselect_b32 s4, s7, s0
	s_cselect_b32 s1, s39, s72
	s_cselect_b32 s0, s41, s49
	s_add_i32 s92, 0, 0x14000
	v_add_u32_e32 v124, s74, v199
	v_add_u32_e32 v140, s92, v199
	ds_read_b128 v[112:115], v124
	ds_read_b128 v[116:119], v124 offset:1024
	ds_read_b128 v[120:123], v124 offset:2048
	ds_read_b128 v[124:127], v124 offset:3072
	ds_read_b128 v[128:131], v140
	ds_read_b128 v[132:135], v140 offset:1024
	ds_read_b128 v[136:139], v140 offset:2048
	ds_read_b128 v[140:143], v140 offset:3072
	s_add_i32 m0, s63, 0xc000
	ds_read_b128 v[172:175], v207
	ds_read_b128 v[178:181], v207 offset:1024
	ds_read_b128 v[186:189], v207 offset:2048
	ds_read_b128 v[190:193], v207 offset:3072
	ds_read_b128 v[194:197], v207 offset:4096
	ds_read_b128 v[200:203], v207 offset:5120
	ds_read_b128 v[208:211], v207 offset:6144
	ds_read_b128 v[212:215], v207 offset:7168
	global_load_lds_dwordx4 v168, s[44:45]
	s_add_i32 m0, s63, 0xe000
	s_nop 0
	global_load_lds_dwordx4 v170, s[44:45]
	s_waitcnt vmcnt(8)
	s_waitcnt lgkmcnt(0)
	s_barrier
	s_waitcnt lgkmcnt(0)
	v_mfma_f32_16x16x32_bf16 v[156:159], v[112:115], v[172:175], 0
	v_mfma_f32_16x16x32_bf16 v[152:155], v[120:123], v[172:175], 0
	v_mfma_f32_16x16x32_bf16 v[108:111], v[112:115], v[186:189], 0
	v_mfma_f32_16x16x32_bf16 v[100:103], v[120:123], v[186:189], 0
	v_mfma_f32_16x16x32_bf16 v[92:95], v[112:115], v[194:197], 0
	v_mfma_f32_16x16x32_bf16 v[84:87], v[120:123], v[194:197], 0
	v_mfma_f32_16x16x32_bf16 v[76:79], v[112:115], v[208:211], 0
	v_mfma_f32_16x16x32_bf16 v[68:71], v[120:123], v[208:211], 0
	v_mfma_f32_16x16x32_bf16 v[156:159], v[116:119], v[178:181], v[156:159]
	v_mfma_f32_16x16x32_bf16 v[152:155], v[124:127], v[178:181], v[152:155]
	v_mfma_f32_16x16x32_bf16 v[108:111], v[116:119], v[190:193], v[108:111]
	v_mfma_f32_16x16x32_bf16 v[100:103], v[124:127], v[190:193], v[100:103]
	v_mfma_f32_16x16x32_bf16 v[92:95], v[116:119], v[200:203], v[92:95]
	v_mfma_f32_16x16x32_bf16 v[84:87], v[124:127], v[200:203], v[84:87]
	v_mfma_f32_16x16x32_bf16 v[76:79], v[116:119], v[212:215], v[76:79]
	v_mfma_f32_16x16x32_bf16 v[68:71], v[124:127], v[212:215], v[68:71]
	v_mfma_f32_16x16x32_bf16 v[148:151], v[128:131], v[172:175], 0
	v_mfma_f32_16x16x32_bf16 v[144:147], v[136:139], v[172:175], 0
	v_mfma_f32_16x16x32_bf16 v[104:107], v[128:131], v[186:189], 0
	v_mfma_f32_16x16x32_bf16 v[96:99], v[136:139], v[186:189], 0
	v_mfma_f32_16x16x32_bf16 v[88:91], v[128:131], v[194:197], 0
	v_mfma_f32_16x16x32_bf16 v[80:83], v[136:139], v[194:197], 0
	v_mfma_f32_16x16x32_bf16 v[72:75], v[128:131], v[208:211], 0
	v_mfma_f32_16x16x32_bf16 v[64:67], v[136:139], v[208:211], 0
	v_mfma_f32_16x16x32_bf16 v[148:151], v[132:135], v[178:181], v[148:151]
	v_mfma_f32_16x16x32_bf16 v[144:147], v[140:143], v[178:181], v[144:147]
	v_mfma_f32_16x16x32_bf16 v[104:107], v[132:135], v[190:193], v[104:107]
	v_mfma_f32_16x16x32_bf16 v[96:99], v[140:143], v[190:193], v[96:99]
	v_mfma_f32_16x16x32_bf16 v[88:91], v[132:135], v[200:203], v[88:91]
	v_mfma_f32_16x16x32_bf16 v[80:83], v[140:143], v[200:203], v[80:83]
	v_mfma_f32_16x16x32_bf16 v[72:75], v[132:135], v[212:215], v[72:75]
	v_mfma_f32_16x16x32_bf16 v[64:67], v[140:143], v[212:215], v[64:67]
	s_barrier
	s_add_i32 s74, s74, s62
	v_lshl_add_u64 v[182:183], s[0:1], 0, v[164:165]
	s_mov_b32 m0, s74
	ds_read_b128 v[172:175], v207 offset:16384
	ds_read_b128 v[178:181], v207 offset:17408
	ds_read_b128 v[186:189], v207 offset:18432
	ds_read_b128 v[190:193], v207 offset:19456
	ds_read_b128 v[194:197], v207 offset:20480
	ds_read_b128 v[200:203], v207 offset:21504
	ds_read_b128 v[208:211], v207 offset:22528
	ds_read_b128 v[212:215], v207 offset:23552
	global_load_lds_dwordx4 v164, s[0:1]
	s_add_i32 m0, s74, 0x2000
	s_add_u32 s74, s0, 0x40000
	v_lshl_add_u64 v[204:205], s[0:1], 0, v[160:161]
	s_addc_u32 s75, s1, 0
	s_add_i32 s92, s92, s62
	global_load_lds_dwordx4 v160, s[0:1]
	s_mov_b32 m0, s92
	v_lshl_add_u64 v[218:219], s[4:5], 0, v[162:163]
	global_load_lds_dwordx4 v164, s[74:75]
	s_add_i32 m0, s92, 0x2000
	s_nop 0
	global_load_lds_dwordx4 v160, s[74:75]
	v_lshl_add_u64 v[216:217], s[4:5], 0, v[166:167]
	s_mov_b32 m0, s63
	s_nop 0
	global_load_lds_dwordx4 v166, s[4:5]
	s_mov_b32 m0, s64
	s_nop 0
	global_load_lds_dwordx4 v162, s[4:5]
	s_waitcnt vmcnt(8)
	s_waitcnt lgkmcnt(0)
	s_barrier
	s_waitcnt lgkmcnt(0)
	v_mfma_f32_16x16x32_bf16 v[60:63], v[112:115], v[172:175], 0
	v_mfma_f32_16x16x32_bf16 v[56:59], v[120:123], v[172:175], 0
	v_mfma_f32_16x16x32_bf16 v[44:47], v[112:115], v[186:189], 0
	v_mfma_f32_16x16x32_bf16 v[36:39], v[120:123], v[186:189], 0
	v_mfma_f32_16x16x32_bf16 v[28:31], v[112:115], v[194:197], 0
	v_mfma_f32_16x16x32_bf16 v[20:23], v[120:123], v[194:197], 0
	v_mfma_f32_16x16x32_bf16 v[12:15], v[112:115], v[208:211], 0
	v_mfma_f32_16x16x32_bf16 v[4:7], v[120:123], v[208:211], 0
	v_mfma_f32_16x16x32_bf16 v[60:63], v[116:119], v[178:181], v[60:63]
	v_mfma_f32_16x16x32_bf16 v[56:59], v[124:127], v[178:181], v[56:59]
	v_mfma_f32_16x16x32_bf16 v[44:47], v[116:119], v[190:193], v[44:47]
	v_mfma_f32_16x16x32_bf16 v[36:39], v[124:127], v[190:193], v[36:39]
	v_mfma_f32_16x16x32_bf16 v[28:31], v[116:119], v[200:203], v[28:31]
	v_mfma_f32_16x16x32_bf16 v[20:23], v[124:127], v[200:203], v[20:23]
	v_mfma_f32_16x16x32_bf16 v[12:15], v[116:119], v[212:215], v[12:15]
	v_mfma_f32_16x16x32_bf16 v[4:7], v[124:127], v[212:215], v[4:7]
	v_mfma_f32_16x16x32_bf16 v[52:55], v[128:131], v[172:175], 0
	v_mfma_f32_16x16x32_bf16 v[48:51], v[136:139], v[172:175], 0
	v_mfma_f32_16x16x32_bf16 v[40:43], v[128:131], v[186:189], 0
	v_mfma_f32_16x16x32_bf16 v[32:35], v[136:139], v[186:189], 0
	v_mfma_f32_16x16x32_bf16 v[24:27], v[128:131], v[194:197], 0
	v_mfma_f32_16x16x32_bf16 v[16:19], v[136:139], v[194:197], 0
	v_mfma_f32_16x16x32_bf16 v[8:11], v[128:131], v[208:211], 0
	v_mfma_f32_16x16x32_bf16 v[0:3], v[136:139], v[208:211], 0
	v_mfma_f32_16x16x32_bf16 v[52:55], v[132:135], v[178:181], v[52:55]
	v_mfma_f32_16x16x32_bf16 v[48:51], v[140:143], v[178:181], v[48:51]
	v_mfma_f32_16x16x32_bf16 v[40:43], v[132:135], v[190:193], v[40:43]
	v_mfma_f32_16x16x32_bf16 v[32:35], v[140:143], v[190:193], v[32:35]
	v_mfma_f32_16x16x32_bf16 v[24:27], v[132:135], v[200:203], v[24:27]
	v_mfma_f32_16x16x32_bf16 v[16:19], v[140:143], v[200:203], v[16:19]
	v_mfma_f32_16x16x32_bf16 v[8:11], v[132:135], v[212:215], v[8:11]
	v_mfma_f32_16x16x32_bf16 v[0:3], v[140:143], v[212:215], v[0:3]
	s_barrier
	s_add_i32 s74, 0, 0x18000
	s_add_i32 s75, 0, 0x1c000
	v_add_u32_e32 v124, s74, v199
	v_add_u32_e32 v140, s75, v199
	ds_read_b128 v[112:115], v124
	ds_read_b128 v[116:119], v124 offset:1024
	ds_read_b128 v[120:123], v124 offset:2048
	ds_read_b128 v[124:127], v124 offset:3072
	ds_read_b128 v[128:131], v140
	ds_read_b128 v[132:135], v140 offset:1024
	ds_read_b128 v[136:139], v140 offset:2048
	ds_read_b128 v[140:143], v140 offset:3072
	s_add_u32 s4, s4, 0x40000
	s_addc_u32 s5, s5, 0
	s_mov_b32 m0, s65
	ds_read_b128 v[172:175], v207 offset:32768
	ds_read_b128 v[178:181], v207 offset:33792
	ds_read_b128 v[186:189], v207 offset:34816
	ds_read_b128 v[190:193], v207 offset:35840
	ds_read_b128 v[194:197], v207 offset:36864
	ds_read_b128 v[200:203], v207 offset:37888
	ds_read_b128 v[208:211], v207 offset:38912
	ds_read_b128 v[212:215], v207 offset:39936
	global_load_lds_dwordx4 v166, s[4:5]
	s_mov_b32 m0, s66
	s_nop 0
	global_load_lds_dwordx4 v162, s[4:5]
	s_waitcnt vmcnt(8)
	s_waitcnt lgkmcnt(0)
	s_barrier
	s_waitcnt lgkmcnt(0)
	v_mfma_f32_16x16x32_bf16 v[156:159], v[112:115], v[172:175], v[156:159]
	v_mfma_f32_16x16x32_bf16 v[152:155], v[120:123], v[172:175], v[152:155]
	v_mfma_f32_16x16x32_bf16 v[108:111], v[112:115], v[186:189], v[108:111]
	v_mfma_f32_16x16x32_bf16 v[100:103], v[120:123], v[186:189], v[100:103]
	v_mfma_f32_16x16x32_bf16 v[92:95], v[112:115], v[194:197], v[92:95]
	v_mfma_f32_16x16x32_bf16 v[84:87], v[120:123], v[194:197], v[84:87]
	v_mfma_f32_16x16x32_bf16 v[76:79], v[112:115], v[208:211], v[76:79]
	v_mfma_f32_16x16x32_bf16 v[68:71], v[120:123], v[208:211], v[68:71]
	v_mfma_f32_16x16x32_bf16 v[156:159], v[116:119], v[178:181], v[156:159]
	v_mfma_f32_16x16x32_bf16 v[152:155], v[124:127], v[178:181], v[152:155]
	v_mfma_f32_16x16x32_bf16 v[108:111], v[116:119], v[190:193], v[108:111]
	v_mfma_f32_16x16x32_bf16 v[100:103], v[124:127], v[190:193], v[100:103]
	v_mfma_f32_16x16x32_bf16 v[92:95], v[116:119], v[200:203], v[92:95]
	v_mfma_f32_16x16x32_bf16 v[84:87], v[124:127], v[200:203], v[84:87]
	v_mfma_f32_16x16x32_bf16 v[76:79], v[116:119], v[212:215], v[76:79]
	v_mfma_f32_16x16x32_bf16 v[68:71], v[124:127], v[212:215], v[68:71]
	v_mfma_f32_16x16x32_bf16 v[148:151], v[128:131], v[172:175], v[148:151]
	v_mfma_f32_16x16x32_bf16 v[144:147], v[136:139], v[172:175], v[144:147]
	v_mfma_f32_16x16x32_bf16 v[104:107], v[128:131], v[186:189], v[104:107]
	v_mfma_f32_16x16x32_bf16 v[96:99], v[136:139], v[186:189], v[96:99]
	v_mfma_f32_16x16x32_bf16 v[88:91], v[128:131], v[194:197], v[88:91]
	v_mfma_f32_16x16x32_bf16 v[80:83], v[136:139], v[194:197], v[80:83]
	v_mfma_f32_16x16x32_bf16 v[72:75], v[128:131], v[208:211], v[72:75]
	v_mfma_f32_16x16x32_bf16 v[64:67], v[136:139], v[208:211], v[64:67]
	v_mfma_f32_16x16x32_bf16 v[148:151], v[132:135], v[178:181], v[148:151]
	v_mfma_f32_16x16x32_bf16 v[144:147], v[140:143], v[178:181], v[144:147]
	v_mfma_f32_16x16x32_bf16 v[104:107], v[132:135], v[190:193], v[104:107]
	v_mfma_f32_16x16x32_bf16 v[96:99], v[140:143], v[190:193], v[96:99]
	v_mfma_f32_16x16x32_bf16 v[88:91], v[132:135], v[200:203], v[88:91]
	v_mfma_f32_16x16x32_bf16 v[80:83], v[140:143], v[200:203], v[80:83]
	v_mfma_f32_16x16x32_bf16 v[72:75], v[132:135], v[212:215], v[72:75]
	v_mfma_f32_16x16x32_bf16 v[64:67], v[140:143], v[212:215], v[64:67]
	s_barrier
	s_add_i32 s4, s74, s62
	v_lshl_add_u64 v[182:183], v[182:183], 0, s[82:83]
	s_mov_b32 m0, s4
	ds_read_b128 v[172:175], v207 offset:49152
	ds_read_b128 v[178:181], v207 offset:50176
	ds_read_b128 v[186:189], v207 offset:51200
	ds_read_b128 v[190:193], v207 offset:52224
	ds_read_b128 v[194:197], v207 offset:53248
	ds_read_b128 v[200:203], v207 offset:54272
	ds_read_b128 v[208:211], v207 offset:55296
	ds_read_b128 v[212:215], v207 offset:56320
	global_load_lds_dwordx4 v[182:183], off
	s_add_i32 m0, s4, 0x2000
	s_add_u32 s0, s0, 0x40080
	v_lshl_add_u64 v[182:183], v[204:205], 0, s[82:83]
	s_addc_u32 s1, s1, 0
	s_add_i32 s4, s75, s62
	global_load_lds_dwordx4 v[182:183], off
	s_mov_b32 m0, s4
	s_nop 0
	global_load_lds_dwordx4 v164, s[0:1]
	s_add_i32 m0, s4, 0x2000
	s_nop 0
	global_load_lds_dwordx4 v160, s[0:1]
	v_lshl_add_u64 v[182:183], v[216:217], 0, s[82:83]
	s_mov_b32 m0, s69
	s_nop 0
	global_load_lds_dwordx4 v[182:183], off
	v_lshl_add_u64 v[182:183], v[218:219], 0, s[82:83]
	s_mov_b32 m0, s70
	s_nop 0
	global_load_lds_dwordx4 v[182:183], off
	s_waitcnt vmcnt(8)
	s_waitcnt lgkmcnt(0)
	s_barrier
	s_waitcnt lgkmcnt(0)
	v_mfma_f32_16x16x32_bf16 v[60:63], v[112:115], v[172:175], v[60:63]
	v_mfma_f32_16x16x32_bf16 v[56:59], v[120:123], v[172:175], v[56:59]
	v_mfma_f32_16x16x32_bf16 v[44:47], v[112:115], v[186:189], v[44:47]
	v_mfma_f32_16x16x32_bf16 v[36:39], v[120:123], v[186:189], v[36:39]
	v_mfma_f32_16x16x32_bf16 v[28:31], v[112:115], v[194:197], v[28:31]
	v_mfma_f32_16x16x32_bf16 v[20:23], v[120:123], v[194:197], v[20:23]
	v_mfma_f32_16x16x32_bf16 v[12:15], v[112:115], v[208:211], v[12:15]
	v_mfma_f32_16x16x32_bf16 v[4:7], v[120:123], v[208:211], v[4:7]
	v_mfma_f32_16x16x32_bf16 v[60:63], v[116:119], v[178:181], v[60:63]
	v_mfma_f32_16x16x32_bf16 v[56:59], v[124:127], v[178:181], v[56:59]
	v_mfma_f32_16x16x32_bf16 v[44:47], v[116:119], v[190:193], v[44:47]
	v_mfma_f32_16x16x32_bf16 v[36:39], v[124:127], v[190:193], v[36:39]
	v_mfma_f32_16x16x32_bf16 v[28:31], v[116:119], v[200:203], v[28:31]
	v_mfma_f32_16x16x32_bf16 v[20:23], v[124:127], v[200:203], v[20:23]
	v_mfma_f32_16x16x32_bf16 v[12:15], v[116:119], v[212:215], v[12:15]
	v_mfma_f32_16x16x32_bf16 v[4:7], v[124:127], v[212:215], v[4:7]
	v_mfma_f32_16x16x32_bf16 v[52:55], v[128:131], v[172:175], v[52:55]
	v_mfma_f32_16x16x32_bf16 v[48:51], v[136:139], v[172:175], v[48:51]
	v_mfma_f32_16x16x32_bf16 v[40:43], v[128:131], v[186:189], v[40:43]
	v_mfma_f32_16x16x32_bf16 v[32:35], v[136:139], v[186:189], v[32:35]
	v_mfma_f32_16x16x32_bf16 v[24:27], v[128:131], v[194:197], v[24:27]
	v_mfma_f32_16x16x32_bf16 v[16:19], v[136:139], v[194:197], v[16:19]
	v_mfma_f32_16x16x32_bf16 v[8:11], v[128:131], v[208:211], v[8:11]
	v_mfma_f32_16x16x32_bf16 v[0:3], v[136:139], v[208:211], v[0:3]
	v_mfma_f32_16x16x32_bf16 v[52:55], v[132:135], v[178:181], v[52:55]
	v_mfma_f32_16x16x32_bf16 v[48:51], v[140:143], v[178:181], v[48:51]
	v_mfma_f32_16x16x32_bf16 v[40:43], v[132:135], v[190:193], v[40:43]
	v_mfma_f32_16x16x32_bf16 v[32:35], v[140:143], v[190:193], v[32:35]
	v_mfma_f32_16x16x32_bf16 v[24:27], v[132:135], v[200:203], v[24:27]
	v_mfma_f32_16x16x32_bf16 v[16:19], v[140:143], v[200:203], v[16:19]
	v_mfma_f32_16x16x32_bf16 v[8:11], v[132:135], v[212:215], v[8:11]
	v_mfma_f32_16x16x32_bf16 v[0:3], v[140:143], v[212:215], v[0:3]
	s_barrier
	s_add_i32 s73, s73, 2
	s_add_u32 s44, s44, 0x100
	s_addc_u32 s45, s45, 0
	s_add_u32 s49, s49, 0x100
	s_addc_u32 s72, s72, 0
	s_cmp_gt_u32 s73, 13
	.p2align	6

.LBB0_929:
	s_add_u32 s69, s0, 0x100
	v_mov_b32_e32 v0, 0
	s_addc_u32 s70, s1, 0
	s_mov_b32 s71, -2
	v_mov_b32_e32 v1, v0
	v_mov_b32_e32 v2, v0
	v_mov_b32_e32 v3, v0
	v_mov_b32_e32 v4, v0
	v_mov_b32_e32 v5, v0
	v_mov_b32_e32 v6, v0
	v_mov_b32_e32 v7, v0
	v_mov_b32_e32 v16, v0
	v_mov_b32_e32 v17, v0
	v_mov_b32_e32 v18, v0
	v_mov_b32_e32 v19, v0
	v_mov_b32_e32 v20, v0
	v_mov_b32_e32 v21, v0
	v_mov_b32_e32 v22, v0
	v_mov_b32_e32 v23, v0
	s_waitcnt vmcnt(0)
	v_mov_b32_e32 v32, v0
	v_mov_b32_e32 v33, v0
	v_mov_b32_e32 v34, v0
	v_mov_b32_e32 v35, v0
	v_mov_b32_e32 v36, v0
	v_mov_b32_e32 v37, v0
	v_mov_b32_e32 v38, v0
	v_mov_b32_e32 v39, v0
	v_mov_b32_e32 v48, v0
	v_mov_b32_e32 v49, v0
	v_mov_b32_e32 v50, v0
	v_mov_b32_e32 v51, v0
	v_mov_b32_e32 v52, v0
	v_mov_b32_e32 v53, v0
	v_mov_b32_e32 v54, v0
	v_mov_b32_e32 v55, v0
	v_mov_b32_e32 v8, v0
	v_mov_b32_e32 v9, v0
	v_mov_b32_e32 v10, v0
	v_mov_b32_e32 v11, v0
	v_mov_b32_e32 v12, v0
	v_mov_b32_e32 v13, v0
	v_mov_b32_e32 v14, v0
	v_mov_b32_e32 v15, v0
	v_mov_b32_e32 v24, v0
	v_mov_b32_e32 v25, v0
	v_mov_b32_e32 v26, v0
	v_mov_b32_e32 v27, v0
	v_mov_b32_e32 v28, v0
	v_mov_b32_e32 v29, v0
	v_mov_b32_e32 v30, v0
	v_mov_b32_e32 v31, v0
	v_mov_b32_e32 v40, v0
	v_mov_b32_e32 v41, v0
	v_mov_b32_e32 v42, v0
	v_mov_b32_e32 v43, v0
	v_mov_b32_e32 v44, v0
	v_mov_b32_e32 v45, v0
	v_mov_b32_e32 v46, v0
	v_mov_b32_e32 v47, v0
	v_mov_b32_e32 v56, v0
	v_mov_b32_e32 v57, v0
	v_mov_b32_e32 v58, v0
	v_mov_b32_e32 v59, v0
	v_mov_b32_e32 v60, v0
	v_mov_b32_e32 v61, v0
	v_mov_b32_e32 v62, v0
	v_mov_b32_e32 v63, v0
	v_mov_b32_e32 v64, v0
	v_mov_b32_e32 v65, v0
	v_mov_b32_e32 v66, v0
	v_mov_b32_e32 v67, v0
	v_mov_b32_e32 v68, v0
	v_mov_b32_e32 v69, v0
	v_mov_b32_e32 v70, v0
	v_mov_b32_e32 v71, v0
	v_mov_b32_e32 v80, v0
	v_mov_b32_e32 v81, v0
	v_mov_b32_e32 v82, v0
	v_mov_b32_e32 v83, v0
	v_mov_b32_e32 v84, v0
	v_mov_b32_e32 v85, v0
	v_mov_b32_e32 v86, v0
	v_mov_b32_e32 v87, v0
	v_mov_b32_e32 v96, v0
	v_mov_b32_e32 v97, v0
	v_mov_b32_e32 v98, v0
	v_mov_b32_e32 v99, v0
	v_mov_b32_e32 v100, v0
	v_mov_b32_e32 v101, v0
	v_mov_b32_e32 v102, v0
	v_mov_b32_e32 v103, v0
	v_mov_b32_e32 v112, v0
	v_mov_b32_e32 v113, v0
	v_mov_b32_e32 v114, v0
	v_mov_b32_e32 v115, v0
	v_mov_b32_e32 v116, v0
	v_mov_b32_e32 v117, v0
	v_mov_b32_e32 v118, v0
	v_mov_b32_e32 v119, v0
	v_mov_b32_e32 v72, v0
	v_mov_b32_e32 v73, v0
	v_mov_b32_e32 v74, v0
	v_mov_b32_e32 v75, v0
	v_mov_b32_e32 v76, v0
	v_mov_b32_e32 v77, v0
	v_mov_b32_e32 v78, v0
	v_mov_b32_e32 v79, v0
	v_mov_b32_e32 v88, v0
	v_mov_b32_e32 v89, v0
	v_mov_b32_e32 v90, v0
	v_mov_b32_e32 v91, v0
	v_mov_b32_e32 v92, v0
	v_mov_b32_e32 v93, v0
	v_mov_b32_e32 v94, v0
	v_mov_b32_e32 v95, v0
	v_mov_b32_e32 v104, v0
	v_mov_b32_e32 v105, v0
	v_mov_b32_e32 v106, v0
	v_mov_b32_e32 v107, v0
	v_mov_b32_e32 v108, v0
	v_mov_b32_e32 v109, v0
	v_mov_b32_e32 v110, v0
	v_mov_b32_e32 v111, v0
	v_mov_b32_e32 v120, v0
	v_mov_b32_e32 v121, v0
	v_mov_b32_e32 v122, v0
	v_mov_b32_e32 v123, v0
	v_mov_b32_e32 v124, v0
	v_mov_b32_e32 v125, v0
	v_mov_b32_e32 v126, v0
	v_mov_b32_e32 v127, v0
	.p2align	6
